# t15 with the score-wave QK MFMAs shifted earlier in the softmax stream (first MFMA after 2 VALU, last at 131 of 167)
# speedup vs baseline: 1.0169x; 1.0016x over previous
; __device__ __forceinline__ void partialSM(f32x16& p0, f32x16& p1, float& m_reg, float& mn, float& alpha) {
;     ...
;   float pmax = p0[0];
; #pragma unroll
;   for (int r = 1; r < 16; ++r) pmax = fmaxf(pmax, p0[r]);
; #pragma unroll
;   for (int r = 0; r < 16; ++r) pmax = fmaxf(pmax, p1[r]);
;   { auto rr = __builtin_amdgcn_permlane32_swap(__float_as_uint(pmax), __float_as_uint(pmax), false, false);
;     pmax = fmaxf(__uint_as_float(rr[0]), __uint_as_float(rr[1])); }
;   if (__builtin_expect(__all(pmax - m_reg <= THR / SCALE), 1)) { mn = m_reg; alpha = 1.f; }
;   else { mn = fmaxf(m_reg, pmax); alpha = __builtin_amdgcn_exp2f((m_reg - mn) * C); m_reg = mn; }
;   float mnC = -mn * C;
; #pragma unroll
;   for (int r = 0; r < 16; ++r) p0[r] = fmaf(p0[r], C, mnC);
; #pragma unroll
;   for (int r = 0; r < 16; ++r) p1[r] = fmaf(p1[r], C, mnC);
; #pragma unroll
;   for (int r = 0; r < 16; ++r) p0[r] = __builtin_amdgcn_exp2f(p0[r]);
; }
; __device__ __forceinline__ void finishSM(f32x16& p0, f32x16& p1, float alpha, float& l_reg, bf16x8& pa0, bf16x8& pa1, bf16x8& pa2, bf16x8& pa3) {
; #pragma unroll
;   for (int r = 0; r < 16; ++r) p1[r] = __builtin_amdgcn_exp2f(p1[r]);
;   float ps = 0;
; #pragma unroll
;   for (int r = 0; r < 16; ++r) ps += p0[r];
; #pragma unroll
;   for (int r = 0; r < 16; ++r) ps += p1[r];
;   { auto rr = __builtin_amdgcn_permlane32_swap(__float_as_uint(ps), __float_as_uint(ps), false, false);
;     ps = __uint_as_float(rr[0]) + __uint_as_float(rr[1]); }
;   l_reg = l_reg * alpha + ps;
.LBB0_508:
	s_cmpk_gt_u32 s71, 0x7d
	s_cselect_b64 s[48:49], -1, 0
	s_add_i32 s8, s72, 0xffffe000
	s_cmpk_lt_u32 s71, 0x7e
	s_cselect_b32 s8, s8, 0xfe000
	s_lshl_b64 s[84:85], s[8:9], 1
	s_add_u32 s84, s46, s84
	s_addc_u32 s85, s47, s85
	ds_read_b128 v[200:203], v108
	ds_read_b128 v[204:207], v108 offset:8192
	ds_read_b128 v[208:211], v109
	ds_read_b128 v[212:215], v109 offset:8192
	ds_read_b128 v[216:219], v110
	ds_read_b128 v[220:223], v110 offset:8192
	ds_read_b128 v[224:227], v111
	ds_read_b128 v[228:231], v111 offset:8192
	s_mov_b32 m0, s64
	s_nop 0
	global_load_lds_dwordx4 v0, s[84:85]
	s_mov_b32 m0, s2
	s_nop 0
	global_load_lds_dwordx4 v236, s[84:85]
	s_mov_b32 m0, s3
	s_nop 0
	global_load_lds_dwordx4 v237, s[84:85]
	s_mov_b32 m0, s66
	s_nop 0
	global_load_lds_dwordx4 v238, s[84:85]
	v_max_f32_e32 v99, v19, v19
	v_max_f32_e32 v118, v18, v18
	s_waitcnt lgkmcnt(6)
	v_mfma_f32_32x32x16_bf16 v[50:65], v[200:203], v[66:69], 0
	v_max_f32_e32 v99, v118, v99
	v_max3_f32 v99, v99, v20, v21
	v_max3_f32 v99, v99, v22, v23
	v_max3_f32 v99, v99, v24, v25
	v_max3_f32 v99, v99, v26, v27
	v_max3_f32 v99, v99, v28, v29
	v_mfma_f32_32x32x16_bf16 v[34:49], v[204:207], v[66:69], 0
	ds_read_b128 v[200:203], v113
	ds_read_b128 v[204:207], v113 offset:8192
	v_max3_f32 v99, v99, v30, v31
	v_max3_f32 v99, v99, v32, v33
	v_max3_f32 v99, v99, v2, v3
	v_max3_f32 v99, v99, v4, v5
	v_max3_f32 v99, v99, v6, v7
	v_max3_f32 v99, v99, v8, v9
	v_max3_f32 v99, v99, v10, v11
	v_max3_f32 v99, v99, v12, v13
	s_waitcnt lgkmcnt(6)
	v_mfma_f32_32x32x16_bf16 v[50:65], v[208:211], v[70:73], v[50:65]
	v_max3_f32 v99, v99, v14, v15
	v_max3_f32 v99, v99, v16, v17
	v_mov_b32_e32 v118, v99
	s_nop 1
	v_permlane32_swap_b32_e32 v99, v118
	v_max_f32_e32 v118, v118, v118
	v_max_f32_e32 v99, v99, v99
	v_max_f32_e32 v99, v99, v118
	v_mfma_f32_32x32x16_bf16 v[34:49], v[212:215], v[70:73], v[34:49]
	ds_read_b128 v[208:211], v114
	ds_read_b128 v[212:215], v114 offset:8192
	v_sub_f32_e32 v118, v99, v121
	v_cmp_ge_f32_e32 vcc, s61, v118
	v_max_f32_e32 v119, v121, v121
	s_cmp_eq_u64 vcc, exec
	v_max_f32_e32 v99, v119, v99
	s_cselect_b64 vcc, -1, 0
	v_sub_f32_e32 v119, v121, v99
	v_cndmask_b32_e32 v121, v99, v121, vcc
	s_waitcnt lgkmcnt(6)
	v_mfma_f32_32x32x16_bf16 v[50:65], v[216:219], v[74:77], v[50:65]
	v_mul_f32_e32 v99, 0xbe0293ee, v121
	v_fmamk_f32 v18, v18, 0x3e0293ee, v99
	v_fmamk_f32 v19, v19, 0x3e0293ee, v99
	v_fmamk_f32 v20, v20, 0x3e0293ee, v99
	v_fmamk_f32 v21, v21, 0x3e0293ee, v99
	v_fmamk_f32 v22, v22, 0x3e0293ee, v99
	v_fmamk_f32 v23, v23, 0x3e0293ee, v99
	v_fmamk_f32 v24, v24, 0x3e0293ee, v99
	v_fmamk_f32 v25, v25, 0x3e0293ee, v99
	v_mfma_f32_32x32x16_bf16 v[34:49], v[220:223], v[74:77], v[34:49]
	ds_read_b128 v[216:219], v115
	ds_read_b128 v[220:223], v115 offset:8192
	v_fmamk_f32 v26, v26, 0x3e0293ee, v99
	v_fmamk_f32 v27, v27, 0x3e0293ee, v99
	v_fmamk_f32 v28, v28, 0x3e0293ee, v99
	v_fmamk_f32 v29, v29, 0x3e0293ee, v99
	v_fmamk_f32 v30, v30, 0x3e0293ee, v99
	v_fmamk_f32 v31, v31, 0x3e0293ee, v99
	v_fmamk_f32 v32, v32, 0x3e0293ee, v99
	v_fmamk_f32 v33, v33, 0x3e0293ee, v99
	v_fmamk_f32 v2, v2, 0x3e0293ee, v99
	s_waitcnt lgkmcnt(6)
	v_mfma_f32_32x32x16_bf16 v[50:65], v[224:227], v[78:81], v[50:65]
	v_fmamk_f32 v3, v3, 0x3e0293ee, v99
	v_fmamk_f32 v4, v4, 0x3e0293ee, v99
	v_fmamk_f32 v5, v5, 0x3e0293ee, v99
	v_fmamk_f32 v6, v6, 0x3e0293ee, v99
	v_fmamk_f32 v7, v7, 0x3e0293ee, v99
	v_fmamk_f32 v8, v8, 0x3e0293ee, v99
	v_fmamk_f32 v9, v9, 0x3e0293ee, v99
	v_fmamk_f32 v10, v10, 0x3e0293ee, v99
	v_fmamk_f32 v11, v11, 0x3e0293ee, v99
	v_mfma_f32_32x32x16_bf16 v[34:49], v[228:231], v[78:81], v[34:49]
	ds_read_b128 v[224:227], v116
	ds_read_b128 v[228:231], v116 offset:8192
	v_fmamk_f32 v12, v12, 0x3e0293ee, v99
	v_fmamk_f32 v13, v13, 0x3e0293ee, v99
	v_fmamk_f32 v14, v14, 0x3e0293ee, v99
	v_fmamk_f32 v15, v15, 0x3e0293ee, v99
	v_fmamk_f32 v16, v16, 0x3e0293ee, v99
	v_fmac_f32_e32 v99, 0x3e0293ee, v17
	v_exp_f32_e32 v17, v18
	v_exp_f32_e32 v18, v19
	v_exp_f32_e32 v19, v20
	s_waitcnt lgkmcnt(6)
	v_mfma_f32_32x32x16_bf16 v[50:65], v[200:203], v[82:85], v[50:65]
	v_exp_f32_e32 v20, v21
	v_exp_f32_e32 v21, v22
	v_exp_f32_e32 v22, v23
	v_exp_f32_e32 v23, v24
	v_exp_f32_e32 v24, v25
	v_exp_f32_e32 v25, v26
	v_exp_f32_e32 v26, v27
	v_exp_f32_e32 v27, v28
	v_exp_f32_e32 v28, v29
	v_mfma_f32_32x32x16_bf16 v[34:49], v[204:207], v[82:85], v[34:49]
	v_exp_f32_e32 v29, v30
	v_exp_f32_e32 v30, v31
	v_exp_f32_e32 v31, v32
	v_exp_f32_e32 v32, v33
	v_exp_f32_e32 v33, v2
	v_add_f32_e32 v2, 0, v17
	v_add_f32_e32 v2, v18, v2
	v_add_f32_e32 v2, v19, v2
	v_add_f32_e32 v2, v20, v2
	s_waitcnt lgkmcnt(4)
	v_mfma_f32_32x32x16_bf16 v[50:65], v[208:211], v[86:89], v[50:65]
	v_add_f32_e32 v2, v21, v2
	v_add_f32_e32 v2, v22, v2
	v_add_f32_e32 v2, v23, v2
	v_add_f32_e32 v2, v24, v2
	v_add_f32_e32 v2, v25, v2
	v_add_f32_e32 v2, v26, v2
	v_add_f32_e32 v2, v27, v2
	v_add_f32_e32 v2, v28, v2
	v_add_f32_e32 v2, v29, v2
	v_mfma_f32_32x32x16_bf16 v[34:49], v[212:215], v[86:89], v[34:49]
	v_exp_f32_e32 v122, v3
	v_add_f32_e32 v2, v30, v2
	v_exp_f32_e32 v123, v4
	v_add_f32_e32 v2, v31, v2
	v_exp_f32_e32 v124, v5
	v_add_f32_e32 v2, v32, v2
	v_exp_f32_e32 v125, v6
	v_add_f32_e32 v2, v33, v2
	v_exp_f32_e32 v126, v7
	s_waitcnt lgkmcnt(2)
	v_mfma_f32_32x32x16_bf16 v[50:65], v[216:219], v[90:93], v[50:65]
	v_add_f32_e32 v2, v122, v2
	v_exp_f32_e32 v127, v8
	v_add_f32_e32 v2, v123, v2
	v_exp_f32_e32 v128, v9
	v_add_f32_e32 v2, v124, v2
	v_exp_f32_e32 v129, v10
	v_add_f32_e32 v2, v125, v2
	v_exp_f32_e32 v130, v11
	v_add_f32_e32 v2, v126, v2
	v_mfma_f32_32x32x16_bf16 v[34:49], v[220:223], v[90:93], v[34:49]
	v_exp_f32_e32 v131, v12
	v_add_f32_e32 v2, v127, v2
	v_exp_f32_e32 v132, v13
	v_add_f32_e32 v2, v128, v2
	v_mul_f32_e32 v119, 0x3e0293ee, v119
	v_exp_f32_e32 v133, v14
	v_add_f32_e32 v2, v129, v2
	v_exp_f32_e32 v119, v119
	v_exp_f32_e32 v134, v15
	s_waitcnt lgkmcnt(0)
; __device__ __forceinline__ void finishSM(f32x16& p0, f32x16& p1, float alpha, float& l_reg, bf16x8& pa0, bf16x8& pa1, bf16x8& pa2, bf16x8& pa3) {
; #pragma unroll
;   for (int r = 0; r < 16; ++r) p1[r] = __builtin_amdgcn_exp2f(p1[r]);
;   float ps = 0;
; #pragma unroll
;   for (int r = 0; r < 16; ++r) ps += p0[r];
; #pragma unroll
;   for (int r = 0; r < 16; ++r) ps += p1[r];
;   { auto rr = __builtin_amdgcn_permlane32_swap(__float_as_uint(ps), __float_as_uint(ps), false, false);
;     ps = __uint_as_float(rr[0]) + __uint_as_float(rr[1]); }
;   l_reg = l_reg * alpha + ps;
;     ...
;   PK4(p0, 0, pa0); PK4(p0, 8, pa1); PK4(p1, 0, pa2); PK4(p1, 8, pa3);
	v_mfma_f32_32x32x16_bf16 v[50:65], v[224:227], v[94:97], v[50:65]
	v_add_f32_e32 v2, v130, v2
	v_exp_f32_e32 v135, v16
	v_add_f32_e32 v2, v131, v2
	v_exp_f32_e32 v99, v99
	v_add_f32_e32 v2, v132, v2
	v_add_f32_e32 v2, v133, v2
	v_cndmask_b32_e64 v118, v119, 1.0, vcc
	v_add_f32_e32 v2, v134, v2
	v_add_f32_e32 v2, v135, v2
	v_mfma_f32_32x32x16_bf16 v[34:49], v[228:231], v[94:97], v[34:49]
	v_cmp_gt_f32_e32 vcc, 1.0, v118
	v_add_f32_e32 v119, v99, v2
	s_cmp_lg_u64 vcc, 0
	v_mov_b32_e32 v120, v119
	v_cvt_pk_bf16_f32 v2, v17, v18
	v_cvt_pk_bf16_f32 v3, v19, v20
	v_cvt_pk_bf16_f32 v4, v21, v22
	v_cvt_pk_bf16_f32 v5, v23, v24
	s_cselect_b64 s[50:51], -1, 0
	s_nop 0
	v_permlane32_swap_b32_e32 v119, v120
	v_permlane32_swap_b32_e32 v2, v4
	v_permlane32_swap_b32_e32 v3, v5
	v_cvt_pk_bf16_f32 v6, v25, v26
	v_cvt_pk_bf16_f32 v7, v27, v28
	v_cvt_pk_bf16_f32 v8, v29, v30
	v_cvt_pk_bf16_f32 v9, v31, v32
	v_cvt_pk_bf16_f32 v10, v33, v122
	v_cvt_pk_bf16_f32 v11, v123, v124
	v_cvt_pk_bf16_f32 v12, v125, v126
	v_cvt_pk_bf16_f32 v13, v127, v128
	v_cvt_pk_bf16_f32 v14, v129, v130
	v_cvt_pk_bf16_f32 v15, v131, v132
	v_cvt_pk_bf16_f32 v16, v133, v134
	v_cvt_pk_bf16_f32 v17, v135, v99
	s_and_b64 s[74:75], s[50:51], s[0:1]
	v_permlane32_swap_b32_e32 v6, v8
	v_permlane32_swap_b32_e32 v7, v9
	v_permlane32_swap_b32_e32 v10, v12
	v_permlane32_swap_b32_e32 v11, v13
	v_permlane32_swap_b32_e32 v14, v16
	v_permlane32_swap_b32_e32 v15, v17
	ds_write_b128 v179, v[2:5]
	ds_write_b128 v179, v[6:9] offset:1024
	ds_write_b128 v179, v[10:13] offset:2048
	ds_write_b128 v179, v[14:17] offset:3072
	s_and_saveexec_b64 s[52:53], s[74:75]
	ds_write_b32 v117, v118
	s_or_b64 exec, exec, s[52:53]
	s_and_saveexec_b64 s[52:53], s[4:5]
	v_cndmask_b32_e64 v2, 0, 1.0, s[50:51]
	v_mov_b32_e32 v3, s65
	ds_write_b32 v3, v2 offset:128
	s_or_b64 exec, exec, s[52:53]
	s_waitcnt vmcnt(0)
	s_waitcnt lgkmcnt(0)
	s_barrier
	s_cmpk_lt_u32 s71, 0x7d
	s_cselect_b32 s8, s72, 0xfe000
	s_lshl_b64 s[84:85], s[8:9], 1
	s_add_u32 s84, s46, s84
	s_addc_u32 s85, s47, s85
	ds_read_b128 v[200:203], v100
	ds_read_b128 v[204:207], v100 offset:8192
	ds_read_b128 v[208:211], v101
	ds_read_b128 v[212:215], v101 offset:8192
	ds_read_b128 v[216:219], v102
	ds_read_b128 v[220:223], v102 offset:8192
	ds_read_b128 v[224:227], v103
	ds_read_b128 v[228:231], v103 offset:8192
	s_mov_b32 m0, s67
	s_nop 0
	global_load_lds_dwordx4 v0, s[84:85]
	s_mov_b32 m0, s68
	s_nop 0
	global_load_lds_dwordx4 v236, s[84:85]
	s_mov_b32 m0, s69
	s_nop 0
	global_load_lds_dwordx4 v237, s[84:85]
	s_mov_b32 m0, s70
	s_nop 0
	global_load_lds_dwordx4 v238, s[84:85]
	v_max_f32_e32 v99, v51, v51
	v_max_f32_e32 v122, v50, v50
	s_waitcnt lgkmcnt(6)
	v_mfma_f32_32x32x16_bf16 v[18:33], v[200:203], v[66:69], 0
	v_max_f32_e32 v99, v122, v99
	v_max3_f32 v99, v99, v52, v53
	v_max3_f32 v99, v99, v54, v55
	v_max3_f32 v99, v99, v56, v57
	v_max3_f32 v99, v99, v58, v59
	v_max3_f32 v99, v99, v60, v61
	v_mfma_f32_32x32x16_bf16 v[2:17], v[204:207], v[66:69], 0
	ds_read_b128 v[200:203], v104
	ds_read_b128 v[204:207], v104 offset:8192
	v_max3_f32 v99, v99, v62, v63
	v_max3_f32 v99, v99, v64, v65
	v_max3_f32 v99, v99, v34, v35
	v_max3_f32 v99, v99, v36, v37
	v_max3_f32 v99, v99, v38, v39
	v_max3_f32 v99, v99, v40, v41
	v_max3_f32 v99, v99, v42, v43
	v_max3_f32 v99, v99, v44, v45
	s_waitcnt lgkmcnt(6)
	v_mfma_f32_32x32x16_bf16 v[18:33], v[208:211], v[70:73], v[18:33]
	v_max3_f32 v99, v99, v46, v47
	v_max3_f32 v99, v99, v48, v49
	v_mov_b32_e32 v122, v99
	s_nop 1
	v_permlane32_swap_b32_e32 v99, v122
	v_max_f32_e32 v122, v122, v122
	v_max_f32_e32 v99, v99, v99
	v_max_f32_e32 v99, v99, v122
	v_mfma_f32_32x32x16_bf16 v[2:17], v[212:215], v[70:73], v[2:17]
	ds_read_b128 v[208:211], v105
	ds_read_b128 v[212:215], v105 offset:8192
	v_sub_f32_e32 v122, v99, v121
	v_cmp_ge_f32_e32 vcc, s61, v122
	v_max_f32_e32 v123, v121, v121
	s_cmp_eq_u64 vcc, exec
	v_max_f32_e32 v123, v123, v99
	s_cselect_b64 vcc, -1, 0
	v_sub_f32_e32 v99, v121, v123
	v_cndmask_b32_e32 v121, v123, v121, vcc
	s_waitcnt lgkmcnt(6)
	v_mfma_f32_32x32x16_bf16 v[18:33], v[216:219], v[74:77], v[18:33]
	v_mul_f32_e32 v122, 0xbe0293ee, v121
	v_fmamk_f32 v50, v50, 0x3e0293ee, v122
	v_fmamk_f32 v51, v51, 0x3e0293ee, v122
	v_fmamk_f32 v52, v52, 0x3e0293ee, v122
	v_fmamk_f32 v53, v53, 0x3e0293ee, v122
	v_fmamk_f32 v54, v54, 0x3e0293ee, v122
	v_fmamk_f32 v55, v55, 0x3e0293ee, v122
	v_fmamk_f32 v56, v56, 0x3e0293ee, v122
	v_fmamk_f32 v57, v57, 0x3e0293ee, v122
	v_mfma_f32_32x32x16_bf16 v[2:17], v[220:223], v[74:77], v[2:17]
	ds_read_b128 v[216:219], v106
	ds_read_b128 v[220:223], v106 offset:8192
	v_fmamk_f32 v58, v58, 0x3e0293ee, v122
	v_fmamk_f32 v59, v59, 0x3e0293ee, v122
	v_fmamk_f32 v60, v60, 0x3e0293ee, v122
	v_fmamk_f32 v61, v61, 0x3e0293ee, v122
	v_fmamk_f32 v62, v62, 0x3e0293ee, v122
	v_fmamk_f32 v63, v63, 0x3e0293ee, v122
	v_fmamk_f32 v64, v64, 0x3e0293ee, v122
	v_fmamk_f32 v65, v65, 0x3e0293ee, v122
	v_fmamk_f32 v34, v34, 0x3e0293ee, v122
	s_waitcnt lgkmcnt(6)
; #define RS_BAR() do { asm volatile("s_waitcnt lgkmcnt(0)" ::: "memory"); __builtin_amdgcn_s_barrier(); asm volatile("" ::: "memory"); } while (0)
; #define KDMA(t, kb) do { _Pragma("unroll") for (int i = 0; i < 4; ++i) \
;       __builtin_amdgcn_global_load_lds((const unsigned*)(Kc + (long)(t) * 8192 + kdo[i]), (ATT_LAS unsigned*)(lds + RS_K + (kb) * 16384 + (pw * 4 + i) * 1024), 16, 0, 0); } while (0)
; #define VM0() asm volatile("s_waitcnt vmcnt(0)" ::: "memory")
; #define VM0() asm volatile("s_waitcnt vmcnt(0)" ::: "memory")
; __device__ __forceinline__ void partialSM(f32x16& p0, f32x16& p1, float& m_reg, float& mn, float& alpha) {
;     ...
;   else { mn = fmaxf(m_reg, pmax); alpha = __builtin_amdgcn_exp2f((m_reg - mn) * C); m_reg = mn; }
;   float mnC = -mn * C;
; #pragma unroll
;   for (int r = 0; r < 16; ++r) p0[r] = fmaf(p0[r], C, mnC);
; #pragma unroll
;   for (int r = 0; r < 16; ++r) p1[r] = fmaf(p1[r], C, mnC);
; #pragma unroll
;   for (int r = 0; r < 16; ++r) p0[r] = __builtin_amdgcn_exp2f(p0[r]);
; }
; __device__ __forceinline__ void finishSM(f32x16& p0, f32x16& p1, float alpha, float& l_reg, bf16x8& pa0, bf16x8& pa1, bf16x8& pa2, bf16x8& pa3) {
; #pragma unroll
;   for (int r = 0; r < 16; ++r) p1[r] = __builtin_amdgcn_exp2f(p1[r]);
;   float ps = 0;
; #pragma unroll
;   for (int r = 0; r < 16; ++r) ps += p0[r];
; #pragma unroll
;   for (int r = 0; r < 16; ++r) ps += p1[r];
;   { auto rr = __builtin_amdgcn_permlane32_swap(__float_as_uint(ps), __float_as_uint(ps), false, false);
;     ps = __uint_as_float(rr[0]) + __uint_as_float(rr[1]); }
;   l_reg = l_reg * alpha + ps;
;     ...
;   PK4(p0, 0, pa0); PK4(p0, 8, pa1); PK4(p1, 0, pa2); PK4(p1, 8, pa3);
; template <class Epi>
; __device__ __forceinline__ void attn_rs_body(const bf16* __restrict__ Qb, const bf16* __restrict__ Kc, const bf16* __restrict__ V0c, const bf16* __restrict__ V1c, int NT, char* lds, const Epi& epi) {
;     ...
;     float m_reg = -1e30f, l_reg = 0.f;
;     f32x16 pA0, pA1, pB0, pB1;
;     KDMA(0, 0); KDMA(1, 1); VM0();
;     RS_BAR();
;     QKT_PF(pA0, pA1, 0);
;     RS_BAR();
	v_mfma_f32_32x32x16_bf16 v[18:33], v[224:227], v[78:81], v[18:33]
	v_fmamk_f32 v35, v35, 0x3e0293ee, v122
	v_fmamk_f32 v36, v36, 0x3e0293ee, v122
	v_fmamk_f32 v37, v37, 0x3e0293ee, v122
	v_fmamk_f32 v38, v38, 0x3e0293ee, v122
	v_fmamk_f32 v39, v39, 0x3e0293ee, v122
	v_fmamk_f32 v40, v40, 0x3e0293ee, v122
	v_fmamk_f32 v41, v41, 0x3e0293ee, v122
	v_fmamk_f32 v42, v42, 0x3e0293ee, v122
	v_fmamk_f32 v43, v43, 0x3e0293ee, v122
	v_mfma_f32_32x32x16_bf16 v[2:17], v[228:231], v[78:81], v[2:17]
	ds_read_b128 v[224:227], v107
	ds_read_b128 v[228:231], v107 offset:8192
	v_fmamk_f32 v44, v44, 0x3e0293ee, v122
	v_fmamk_f32 v45, v45, 0x3e0293ee, v122
	v_fmamk_f32 v46, v46, 0x3e0293ee, v122
	v_fmamk_f32 v47, v47, 0x3e0293ee, v122
	v_fmamk_f32 v48, v48, 0x3e0293ee, v122
	v_fmac_f32_e32 v122, 0x3e0293ee, v49
	v_exp_f32_e32 v49, v50
	v_exp_f32_e32 v50, v51
	v_exp_f32_e32 v51, v52
	s_waitcnt lgkmcnt(6)
	v_mfma_f32_32x32x16_bf16 v[18:33], v[200:203], v[82:85], v[18:33]
	v_exp_f32_e32 v52, v53
	v_exp_f32_e32 v53, v54
	v_exp_f32_e32 v54, v55
	v_exp_f32_e32 v55, v56
	v_exp_f32_e32 v56, v57
	v_exp_f32_e32 v57, v58
	v_exp_f32_e32 v58, v59
	v_exp_f32_e32 v59, v60
	v_exp_f32_e32 v60, v61
	v_mfma_f32_32x32x16_bf16 v[2:17], v[204:207], v[82:85], v[2:17]
	v_exp_f32_e32 v61, v62
	v_exp_f32_e32 v62, v63
	v_exp_f32_e32 v63, v64
	v_exp_f32_e32 v64, v65
	v_exp_f32_e32 v65, v34
	v_add_f32_e32 v34, 0, v49
	v_add_f32_e32 v34, v50, v34
	v_add_f32_e32 v34, v51, v34
	v_add_f32_e32 v34, v52, v34
	s_waitcnt lgkmcnt(4)
	v_mfma_f32_32x32x16_bf16 v[18:33], v[208:211], v[86:89], v[18:33]
	v_add_f32_e32 v34, v53, v34
	v_add_f32_e32 v34, v54, v34
	v_add_f32_e32 v34, v55, v34
	v_add_f32_e32 v34, v56, v34
	v_add_f32_e32 v34, v57, v34
	v_add_f32_e32 v34, v58, v34
	v_add_f32_e32 v34, v59, v34
	v_add_f32_e32 v34, v60, v34
	v_add_f32_e32 v34, v61, v34
	v_mfma_f32_32x32x16_bf16 v[2:17], v[212:215], v[86:89], v[2:17]
	v_exp_f32_e32 v123, v35
	v_add_f32_e32 v34, v62, v34
	v_exp_f32_e32 v124, v36
	v_add_f32_e32 v34, v63, v34
	v_exp_f32_e32 v125, v37
	v_add_f32_e32 v34, v64, v34
	v_exp_f32_e32 v126, v38
	v_add_f32_e32 v34, v65, v34
	v_exp_f32_e32 v127, v39
	s_waitcnt lgkmcnt(2)
	v_mfma_f32_32x32x16_bf16 v[18:33], v[216:219], v[90:93], v[18:33]
	v_add_f32_e32 v34, v123, v34
	v_exp_f32_e32 v128, v40
	v_add_f32_e32 v34, v124, v34
	v_exp_f32_e32 v129, v41
	v_add_f32_e32 v34, v125, v34
	v_exp_f32_e32 v130, v42
	v_add_f32_e32 v34, v126, v34
	v_exp_f32_e32 v131, v43
	v_add_f32_e32 v34, v127, v34
	v_mfma_f32_32x32x16_bf16 v[2:17], v[220:223], v[90:93], v[2:17]
	v_exp_f32_e32 v132, v44
	v_add_f32_e32 v34, v128, v34
	v_exp_f32_e32 v133, v45
	v_add_f32_e32 v34, v129, v34
	v_mul_f32_e32 v99, 0x3e0293ee, v99
	v_exp_f32_e32 v134, v46
	v_add_f32_e32 v34, v130, v34
	v_exp_f32_e32 v99, v99
	v_exp_f32_e32 v135, v47
	s_waitcnt lgkmcnt(0)
	v_mfma_f32_32x32x16_bf16 v[18:33], v[224:227], v[94:97], v[18:33]
	v_add_f32_e32 v34, v131, v34
	v_exp_f32_e32 v136, v48
	v_add_f32_e32 v34, v132, v34
	v_exp_f32_e32 v122, v122
	v_add_f32_e32 v34, v133, v34
	v_add_f32_e32 v34, v134, v34
	v_cndmask_b32_e64 v99, v99, 1.0, vcc
	v_add_f32_e32 v34, v135, v34
	v_add_f32_e32 v34, v136, v34
	v_mfma_f32_32x32x16_bf16 v[2:17], v[228:231], v[94:97], v[2:17]
	v_cmp_gt_f32_e32 vcc, 1.0, v99
	v_add_f32_e32 v34, v122, v34
	s_cmp_lg_u64 vcc, 0
	v_mov_b32_e32 v35, v34
	v_cvt_pk_bf16_f32 v36, v49, v50
	v_cvt_pk_bf16_f32 v37, v51, v52
	v_cvt_pk_bf16_f32 v38, v53, v54
	v_cvt_pk_bf16_f32 v39, v55, v56
	s_cselect_b64 s[50:51], -1, 0
	s_nop 0
	v_permlane32_swap_b32_e32 v34, v35
	v_permlane32_swap_b32_e32 v36, v38
	v_permlane32_swap_b32_e32 v37, v39
	v_cvt_pk_bf16_f32 v40, v57, v58
	v_cvt_pk_bf16_f32 v41, v59, v60
	v_cvt_pk_bf16_f32 v42, v61, v62
	v_cvt_pk_bf16_f32 v43, v63, v64
	v_cvt_pk_bf16_f32 v44, v65, v123
	v_cvt_pk_bf16_f32 v45, v124, v125
	v_cvt_pk_bf16_f32 v46, v126, v127
	v_cvt_pk_bf16_f32 v47, v128, v129
	v_cvt_pk_bf16_f32 v48, v130, v131
	v_cvt_pk_bf16_f32 v49, v132, v133
	v_cvt_pk_bf16_f32 v50, v134, v135
	v_cvt_pk_bf16_f32 v51, v136, v122
	s_and_b64 s[74:75], s[50:51], s[0:1]
	v_permlane32_swap_b32_e32 v40, v42
	v_permlane32_swap_b32_e32 v41, v43
	v_permlane32_swap_b32_e32 v44, v46
	v_permlane32_swap_b32_e32 v45, v47
	v_permlane32_swap_b32_e32 v48, v50
	v_permlane32_swap_b32_e32 v49, v51
	ds_write_b128 v179, v[36:39] offset:16384
	ds_write_b128 v179, v[40:43] offset:17408
	ds_write_b128 v179, v[44:47] offset:18432
	ds_write_b128 v179, v[48:51] offset:19456
	s_and_saveexec_b64 s[52:53], s[74:75]
	ds_write_b32 v117, v99 offset:1024
	s_or_b64 exec, exec, s[52:53]
	s_and_saveexec_b64 s[52:53], s[4:5]
	s_cbranch_execz .LBB0_507
	v_cndmask_b32_e64 v36, 0, 1.0, s[50:51]
	v_mov_b32_e32 v37, s65
	ds_write_b32 v37, v36 offset:1152
	s_branch .LBB0_507
